# grid barrier: non-leader workgroups poll the cross-XCD generation word directly (one polling hop less)
# speedup vs baseline: 1.0035x; 1.0035x over previous
.LBB0_224:
	s_or_b64 exec, exec, s[6:7]
	buffer_inv sc1
	v_cvt_f32_u32_e32 v5, v3
	s_waitcnt vmcnt(1)
	v_readfirstlane_b32 s4, v4
	v_sub_u32_e32 v4, 0, v3
	v_rcp_iflag_f32_e32 v5, v5
	v_add_u32_e32 v6, s4, v2
	v_mul_f32_e32 v5, 0x4f7ffffe, v5
	v_cvt_u32_f32_e32 v5, v5
	v_mul_lo_u32 v2, v4, v5
	v_mul_hi_u32 v2, v5, v2
	v_add_u32_e32 v2, v5, v2
	v_mul_hi_u32 v2, v6, v2
	v_mul_lo_u32 v4, v2, v3
	v_sub_u32_e32 v4, v6, v4
	v_add_u32_e32 v5, 1, v2
	v_cmp_ge_u32_e32 vcc, v4, v3
	s_nop 1
	v_cndmask_b32_e32 v2, v2, v5, vcc
	v_sub_u32_e32 v5, v4, v3
	v_cndmask_b32_e32 v4, v4, v5, vcc
	v_add_u32_e32 v5, 1, v2
	v_cmp_ge_u32_e32 vcc, v4, v3
	v_add_u32_e32 v4, 1, v6
	s_nop 0
	v_cndmask_b32_e32 v2, v2, v5, vcc
	v_mul_lo_u32 v5, v3, v2
	v_add_u32_e32 v3, v5, v3
	v_cmp_ne_u32_e32 vcc, v4, v3
	s_and_saveexec_b64 s[4:5], vcc
	s_xor_b64 s[4:5], exec, s[4:5]
	s_cbranch_execz .LBB0_238
	s_waitcnt lgkmcnt(0)
	s_add_u32 s10, s96, 0x4500
	s_addc_u32 s11, s97, 0
	v_mov_b32_e32 v1, 0
	global_load_dword v1, v1, s[10:11] sc1
	s_sub_i32 s8, 1, s94
	v_mov_b32_e32 v2, s8
	s_waitcnt vmcnt(0)
	v_cmp_gt_u32_e32 vcc, v2, v1
	s_and_saveexec_b64 s[6:7], vcc
	s_cbranch_execz .LBB0_237
	s_add_u32 s8, s96, 0x1200
	s_addc_u32 s9, s97, 0
	s_mov_b32 s22, 1
	s_mov_b64 s[12:13], 0
	v_mov_b32_e32 v1, 0
	s_branch .LBB0_228

.LBB0_230:
	global_load_dword v3, v1, s[10:11] sc1
	s_add_i32 s22, s22, 1
	s_mov_b64 s[18:19], -1
	s_waitcnt vmcnt(0)
	v_cmp_le_u32_e32 vcc, v2, v3
	s_orn2_b64 s[16:17], vcc, exec
	s_branch .LBB0_227

.LBB0_319:
	s_or_b64 exec, exec, s[6:7]
	buffer_inv sc1
	v_cvt_f32_u32_e32 v5, v3
	s_waitcnt vmcnt(1)
	v_readfirstlane_b32 s4, v4
	v_sub_u32_e32 v4, 0, v3
	v_rcp_iflag_f32_e32 v5, v5
	v_add_u32_e32 v6, s4, v2
	v_mul_f32_e32 v5, 0x4f7ffffe, v5
	v_cvt_u32_f32_e32 v5, v5
	v_mul_lo_u32 v2, v4, v5
	v_mul_hi_u32 v2, v5, v2
	v_add_u32_e32 v2, v5, v2
	v_mul_hi_u32 v2, v6, v2
	v_mul_lo_u32 v4, v2, v3
	v_sub_u32_e32 v4, v6, v4
	v_add_u32_e32 v5, 1, v2
	v_cmp_ge_u32_e32 vcc, v4, v3
	s_nop 1
	v_cndmask_b32_e32 v2, v2, v5, vcc
	v_sub_u32_e32 v5, v4, v3
	v_cndmask_b32_e32 v4, v4, v5, vcc
	v_add_u32_e32 v5, 1, v2
	v_cmp_ge_u32_e32 vcc, v4, v3
	v_add_u32_e32 v4, 1, v6
	s_nop 0
	v_cndmask_b32_e32 v2, v2, v5, vcc
	v_mul_lo_u32 v5, v3, v2
	v_add_u32_e32 v3, v5, v3
	v_cmp_ne_u32_e32 vcc, v4, v3
	s_and_saveexec_b64 s[4:5], vcc
	s_xor_b64 s[4:5], exec, s[4:5]
	s_cbranch_execz .LBB0_333
	s_waitcnt lgkmcnt(0)
	s_add_u32 s10, s96, 0x4500
	s_addc_u32 s11, s97, 0
	v_mov_b32_e32 v1, 0
	global_load_dword v1, v1, s[10:11] sc1
	s_sub_i32 s8, 2, s94
	v_mov_b32_e32 v2, s8
	s_waitcnt vmcnt(0)
	v_cmp_gt_u32_e32 vcc, v2, v1
	s_and_saveexec_b64 s[6:7], vcc
	s_cbranch_execz .LBB0_332
	s_add_u32 s8, s96, 0x1200
	s_addc_u32 s9, s97, 0
	s_mov_b32 s22, 1
	s_mov_b64 s[12:13], 0
	v_mov_b32_e32 v1, 0
	s_branch .LBB0_323

.LBB0_445:
	s_or_b64 exec, exec, s[6:7]
	buffer_inv sc1
	v_cvt_f32_u32_e32 v5, v3
	s_waitcnt vmcnt(1)
	v_readfirstlane_b32 s4, v4
	v_sub_u32_e32 v4, 0, v3
	v_rcp_iflag_f32_e32 v5, v5
	v_add_u32_e32 v6, s4, v2
	v_mul_f32_e32 v5, 0x4f7ffffe, v5
	v_cvt_u32_f32_e32 v5, v5
	v_mul_lo_u32 v2, v4, v5
	v_mul_hi_u32 v2, v5, v2
	v_add_u32_e32 v2, v5, v2
	v_mul_hi_u32 v2, v6, v2
	v_mul_lo_u32 v4, v2, v3
	v_sub_u32_e32 v4, v6, v4
	v_add_u32_e32 v5, 1, v2
	v_cmp_ge_u32_e32 vcc, v4, v3
	s_nop 1
	v_cndmask_b32_e32 v2, v2, v5, vcc
	v_sub_u32_e32 v5, v4, v3
	v_cndmask_b32_e32 v4, v4, v5, vcc
	v_add_u32_e32 v5, 1, v2
	v_cmp_ge_u32_e32 vcc, v4, v3
	v_add_u32_e32 v4, 1, v6
	s_nop 0
	v_cndmask_b32_e32 v2, v2, v5, vcc
	v_mul_lo_u32 v5, v3, v2
	v_add_u32_e32 v3, v5, v3
	v_cmp_ne_u32_e32 vcc, v4, v3
	s_and_saveexec_b64 s[4:5], vcc
	s_xor_b64 s[4:5], exec, s[4:5]
	s_cbranch_execz .LBB0_459
	s_waitcnt lgkmcnt(0)
	s_add_u32 s10, s96, 0x4500
	s_addc_u32 s11, s97, 0
	v_mov_b32_e32 v1, 0
	global_load_dword v1, v1, s[10:11] sc1
	s_sub_i32 s8, 3, s94
	v_mov_b32_e32 v2, s8
	s_waitcnt vmcnt(0)
	v_cmp_gt_u32_e32 vcc, v2, v1
	s_and_saveexec_b64 s[6:7], vcc
	s_cbranch_execz .LBB0_458
	s_add_u32 s8, s96, 0x1200
	s_addc_u32 s9, s97, 0
	s_mov_b32 s22, 1
	s_mov_b64 s[12:13], 0
	v_mov_b32_e32 v1, 0
	s_branch .LBB0_449

.LBB0_513:
	s_or_b64 exec, exec, s[6:7]
	buffer_inv sc1
	v_cvt_f32_u32_e32 v5, v3
	s_waitcnt vmcnt(1)
	v_readfirstlane_b32 s4, v4
	v_sub_u32_e32 v4, 0, v3
	v_rcp_iflag_f32_e32 v5, v5
	v_add_u32_e32 v6, s4, v2
	v_mul_f32_e32 v5, 0x4f7ffffe, v5
	v_cvt_u32_f32_e32 v5, v5
	v_mul_lo_u32 v2, v4, v5
	v_mul_hi_u32 v2, v5, v2
	v_add_u32_e32 v2, v5, v2
	v_mul_hi_u32 v2, v6, v2
	v_mul_lo_u32 v4, v2, v3
	v_sub_u32_e32 v4, v6, v4
	v_add_u32_e32 v5, 1, v2
	v_cmp_ge_u32_e32 vcc, v4, v3
	s_nop 1
	v_cndmask_b32_e32 v2, v2, v5, vcc
	v_sub_u32_e32 v5, v4, v3
	v_cndmask_b32_e32 v4, v4, v5, vcc
	v_add_u32_e32 v5, 1, v2
	v_cmp_ge_u32_e32 vcc, v4, v3
	v_add_u32_e32 v4, 1, v6
	s_nop 0
	v_cndmask_b32_e32 v2, v2, v5, vcc
	v_mul_lo_u32 v5, v3, v2
	v_add_u32_e32 v3, v5, v3
	v_cmp_ne_u32_e32 vcc, v4, v3
	s_and_saveexec_b64 s[4:5], vcc
	s_xor_b64 s[4:5], exec, s[4:5]
	s_cbranch_execz .LBB0_527
	s_waitcnt lgkmcnt(0)
	s_add_u32 s10, s96, 0x4500
	s_addc_u32 s11, s97, 0
	v_mov_b32_e32 v1, 0
	global_load_dword v1, v1, s[10:11] sc1
	s_sub_i32 s8, 4, s94
	v_mov_b32_e32 v2, s8
	s_waitcnt vmcnt(0)
	v_cmp_gt_u32_e32 vcc, v2, v1
	s_and_saveexec_b64 s[6:7], vcc
	s_cbranch_execz .LBB0_526
	s_add_u32 s8, s96, 0x1200
	s_addc_u32 s9, s97, 0
	s_mov_b32 s22, 1
	s_mov_b64 s[12:13], 0
	v_mov_b32_e32 v1, 0
	s_branch .LBB0_517

.LBB0_713:
	s_or_b64 exec, exec, s[6:7]
	buffer_inv sc1
	v_cvt_f32_u32_e32 v5, v3
	s_waitcnt vmcnt(1)
	v_readfirstlane_b32 s4, v4
	v_sub_u32_e32 v4, 0, v3
	v_rcp_iflag_f32_e32 v5, v5
	v_add_u32_e32 v6, s4, v2
	v_mul_f32_e32 v5, 0x4f7ffffe, v5
	v_cvt_u32_f32_e32 v5, v5
	v_mul_lo_u32 v2, v4, v5
	v_mul_hi_u32 v2, v5, v2
	v_add_u32_e32 v2, v5, v2
	v_mul_hi_u32 v2, v6, v2
	v_mul_lo_u32 v4, v2, v3
	v_sub_u32_e32 v4, v6, v4
	v_add_u32_e32 v5, 1, v2
	v_cmp_ge_u32_e32 vcc, v4, v3
	s_nop 1
	v_cndmask_b32_e32 v2, v2, v5, vcc
	v_sub_u32_e32 v5, v4, v3
	v_cndmask_b32_e32 v4, v4, v5, vcc
	v_add_u32_e32 v5, 1, v2
	v_cmp_ge_u32_e32 vcc, v4, v3
	v_add_u32_e32 v4, 1, v6
	s_nop 0
	v_cndmask_b32_e32 v2, v2, v5, vcc
	v_mul_lo_u32 v5, v3, v2
	v_add_u32_e32 v3, v5, v3
	v_cmp_ne_u32_e32 vcc, v4, v3
	s_and_saveexec_b64 s[4:5], vcc
	s_xor_b64 s[4:5], exec, s[4:5]
	s_cbranch_execz .LBB0_727
	s_waitcnt lgkmcnt(0)
	s_add_u32 s10, s96, 0x4500
	s_addc_u32 s11, s97, 0
	v_mov_b32_e32 v1, 0
	global_load_dword v1, v1, s[10:11] sc1
	s_sub_i32 s8, 5, s94
	v_mov_b32_e32 v2, s8
	s_waitcnt vmcnt(0)
	v_cmp_gt_u32_e32 vcc, v2, v1
	s_and_saveexec_b64 s[6:7], vcc
	s_cbranch_execz .LBB0_726
	s_add_u32 s8, s96, 0x1200
	s_addc_u32 s9, s97, 0
	s_mov_b32 s22, 1
	s_mov_b64 s[12:13], 0
	v_mov_b32_e32 v1, 0
	s_branch .LBB0_717
